# grid barrier: XCD leaders no longer bump the (now unread) per-XCD generation word
# baseline (speedup 1.0000x reference)
.LBB0_142:
	s_or_b64 exec, exec, s[6:7]
	s_mov_b64 s[6:7], exec
	v_mbcnt_lo_u32_b32 v0, s6, 0
	v_mbcnt_hi_u32_b32 v0, s7, v0
	v_cmp_eq_u32_e32 vcc, 0, v0
	s_waitcnt vmcnt(0)
	buffer_inv sc1
	s_and_saveexec_b64 s[8:9], vcc
	s_cbranch_execz .LBB0_144
	s_bcnt1_i32_b64 s6, s[6:7]
	v_mov_b32_e32 v0, 0x2000
	v_mov_b32_e32 v1, s6
.LBB0_144:
	s_or_b64 exec, exec, s[8:9]
	s_waitcnt vmcnt(0)

.LBB0_331:
	s_or_b64 exec, exec, s[12:13]
	s_mov_b64 s[12:13], exec
	v_mbcnt_lo_u32_b32 v0, s12, 0
	v_mbcnt_hi_u32_b32 v0, s13, v0
	v_cmp_eq_u32_e32 vcc, 0, v0
	s_waitcnt vmcnt(0)
	buffer_inv sc1
	s_and_saveexec_b64 s[14:15], vcc
	s_cbranch_execz .LBB0_333
	s_bcnt1_i32_b64 s12, s[12:13]
	v_mov_b32_e32 v0, 0x2000
	v_mov_b32_e32 v1, s12
.LBB0_333:
	s_or_b64 exec, exec, s[14:15]
	s_waitcnt vmcnt(0)

.LBB0_453:
	s_or_b64 exec, exec, s[12:13]
	s_mov_b64 s[12:13], exec
	v_mbcnt_lo_u32_b32 v0, s12, 0
	v_mbcnt_hi_u32_b32 v0, s13, v0
	v_cmp_eq_u32_e32 vcc, 0, v0
	s_waitcnt vmcnt(0)
	buffer_inv sc1
	s_and_saveexec_b64 s[14:15], vcc
	s_cbranch_execz .LBB0_455
	s_bcnt1_i32_b64 s12, s[12:13]
	v_mov_b32_e32 v0, 0x2000
	v_mov_b32_e32 v1, s12
.LBB0_455:
	s_or_b64 exec, exec, s[14:15]
	s_waitcnt vmcnt(0)

.LBB0_567:
	s_or_b64 exec, exec, s[6:7]
	s_mov_b64 s[6:7], exec
	v_mbcnt_lo_u32_b32 v0, s6, 0
	v_mbcnt_hi_u32_b32 v0, s7, v0
	v_cmp_eq_u32_e32 vcc, 0, v0
	s_waitcnt vmcnt(0)
	buffer_inv sc1
	s_and_saveexec_b64 s[12:13], vcc
	s_cbranch_execz .LBB0_569
	s_bcnt1_i32_b64 s6, s[6:7]
	v_mov_b32_e32 v0, 0x2000
	v_mov_b32_e32 v1, s6
.LBB0_569:
	s_or_b64 exec, exec, s[12:13]
	s_waitcnt vmcnt(0)

.LBB0_664:
	s_or_b64 exec, exec, s[6:7]
	s_mov_b64 s[6:7], exec
	v_mbcnt_lo_u32_b32 v0, s6, 0
	v_mbcnt_hi_u32_b32 v0, s7, v0
	v_cmp_eq_u32_e32 vcc, 0, v0
	s_waitcnt vmcnt(0)
	buffer_inv sc1
	s_and_saveexec_b64 s[12:13], vcc
	s_cbranch_execz .LBB0_666
	s_bcnt1_i32_b64 s6, s[6:7]
	v_mov_b32_e32 v0, 0x2000
	v_mov_b32_e32 v1, s6
.LBB0_666:
	s_or_b64 exec, exec, s[12:13]
	s_waitcnt vmcnt(0)

.LBB0_777:
	s_or_b64 exec, exec, s[6:7]
	s_mov_b64 s[6:7], exec
	v_mbcnt_lo_u32_b32 v0, s6, 0
	v_mbcnt_hi_u32_b32 v0, s7, v0
	v_cmp_eq_u32_e32 vcc, 0, v0
	s_waitcnt vmcnt(0)
	buffer_inv sc1
	s_and_saveexec_b64 s[14:15], vcc
	s_cbranch_execz .LBB0_779
	s_bcnt1_i32_b64 s6, s[6:7]
	v_mov_b32_e32 v0, 0x2000
	v_mov_b32_e32 v1, s6
.LBB0_779:
	s_or_b64 exec, exec, s[14:15]
	s_waitcnt vmcnt(0)

.LBB0_876:
	s_or_b64 exec, exec, s[12:13]
	s_mov_b64 s[12:13], exec
	v_mbcnt_lo_u32_b32 v0, s12, 0
	v_mbcnt_hi_u32_b32 v0, s13, v0
	v_cmp_eq_u32_e32 vcc, 0, v0
	s_waitcnt vmcnt(0)
	buffer_inv sc1
	s_and_saveexec_b64 s[14:15], vcc
	s_cbranch_execz .LBB0_878
	s_bcnt1_i32_b64 s12, s[12:13]
	v_mov_b32_e32 v0, 0x2000
	v_mov_b32_e32 v1, s12
.LBB0_878:
	s_or_b64 exec, exec, s[14:15]
	s_waitcnt vmcnt(0)

.LBB0_947:
	s_or_b64 exec, exec, s[12:13]
	s_mov_b64 s[12:13], exec
	v_mbcnt_lo_u32_b32 v0, s12, 0
	v_mbcnt_hi_u32_b32 v0, s13, v0
	v_cmp_eq_u32_e32 vcc, 0, v0
	s_waitcnt vmcnt(0)
	buffer_inv sc1
	s_and_saveexec_b64 s[14:15], vcc
	s_cbranch_execz .LBB0_949
	s_bcnt1_i32_b64 s12, s[12:13]
	v_mov_b32_e32 v0, 0x2000
	v_mov_b32_e32 v1, s12
.LBB0_949:
	s_or_b64 exec, exec, s[14:15]
	s_waitcnt vmcnt(0)

.LBB0_1048:
	s_or_b64 exec, exec, s[6:7]
	s_mov_b64 s[6:7], exec
	v_mbcnt_lo_u32_b32 v0, s6, 0
	v_mbcnt_hi_u32_b32 v0, s7, v0
	v_cmp_eq_u32_e32 vcc, 0, v0
	s_waitcnt vmcnt(0)
	buffer_inv sc1
	s_and_saveexec_b64 s[10:11], vcc
	s_cbranch_execz .LBB0_1050
	s_bcnt1_i32_b64 s6, s[6:7]
	v_mov_b32_e32 v0, 0x2000
	v_mov_b32_e32 v1, s6
.LBB0_1050:
	s_or_b64 exec, exec, s[10:11]
	s_waitcnt vmcnt(0)
